# attention: compact window mask (2 VALU/elem), K/V fragment reads hoisted with counted lgkmcnt, row-max exchange via v_permlane32_swap instead of ds_bpermute
# speedup vs baseline: 1.0071x; 1.0071x over previous
.LBB0_793:
	v_writelane_b32 v242, s20, 21
	v_writelane_b32 v242, s21, 22
	v_writelane_b32 v242, s22, 23
	v_writelane_b32 v242, s23, 24
	v_writelane_b32 v242, s24, 25
	v_writelane_b32 v242, s25, 26
	s_cmp_ge_i32 s45, s72
	s_cbranch_scc1 .LBB0_828
	v_readlane_b32 s4, v247, 2
	s_lshl_b32 s26, s56, 3
	v_readlane_b32 s5, v247, 3
	v_readlane_b32 s8, v247, 6
	v_readlane_b32 s9, v247, 7
	s_lshl_b64 s[2:3], s[26:27], 2
	s_mov_b64 s[4:5], s[8:9]
	v_readlane_b32 s6, v247, 4
	s_add_u32 s4, s4, s2
	s_addc_u32 s5, s5, s3
	s_mov_b32 s6, s45
	v_readlane_b32 s7, v247, 5
	v_readlane_b32 s10, v247, 8
	v_readlane_b32 s11, v247, 9
	v_readlane_b32 s12, v247, 10
	v_readlane_b32 s13, v247, 11
	v_readlane_b32 s14, v247, 12
	v_readlane_b32 s15, v247, 13
	v_readlane_b32 s16, v247, 14
	v_readlane_b32 s17, v247, 15
	v_readlane_b32 s18, v247, 16
	v_readlane_b32 s19, v247, 17
	s_branch .LBB0_796

.LBB0_816:
	s_setprio 1
	ds_read_b128 v[64:67], v189
	ds_read_b128 v[164:167], v189 offset:32
	ds_read_b128 v[168:171], v189 offset:64
	ds_read_b128 v[172:175], v189 offset:96
	s_waitcnt lgkmcnt(3)
	v_mfma_f32_32x32x16_bf16 v[80:95], v[64:67], v[96:99], 0
	v_mfma_f32_32x32x16_bf16 v[64:79], v[64:67], v[112:115], 0
	s_waitcnt lgkmcnt(2)
	v_mfma_f32_32x32x16_bf16 v[80:95], v[164:167], v[100:103], v[80:95]
	v_mfma_f32_32x32x16_bf16 v[64:79], v[164:167], v[116:119], v[64:79]
	s_waitcnt lgkmcnt(1)
	v_mfma_f32_32x32x16_bf16 v[80:95], v[168:171], v[104:107], v[80:95]
	v_mfma_f32_32x32x16_bf16 v[64:79], v[168:171], v[120:123], v[64:79]
	s_waitcnt lgkmcnt(0)
	v_mfma_f32_32x32x16_bf16 v[80:95], v[172:175], v[108:111], v[80:95]
	v_mfma_f32_32x32x16_bf16 v[64:79], v[172:175], v[124:127], v[64:79]
	s_setprio 0
	s_cmp_lt_i32 s9, 2
	s_cbranch_scc1 .LBB0_818
	s_cmp_eq_u32 s9, 2
	s_cselect_b64 s[50:51], -1, 0
	s_cbranch_execz .LBB0_819
	s_branch .LBB0_820

.LBB0_820:
	s_andn2_b64 vcc, exec, s[50:51]
	s_cbranch_vccnz .LBB0_822
	v_add_u32_e32 v164, s13, v183
	v_sub_u32_e32 v165, v162, v164
	v_add_u32_e32 v166, 32, v165
	s_and_b64 vcc, exec, s[36:37]
	s_cbranch_vccz .Latt_m2
	v_cmp_lt_i32_e64 s[20:21], 0, v165
	v_cmp_lt_i32_e64 s[22:23], 1, v165
	v_cmp_lt_i32_e64 s[24:25], 2, v165
	v_cndmask_b32_e64 v80, v80, v205, s[20:21]
	v_cmp_lt_i32_e64 s[20:21], 3, v165
	v_cndmask_b32_e64 v81, v81, v205, s[22:23]
	v_cmp_lt_i32_e64 s[22:23], 8, v165
	v_cndmask_b32_e64 v82, v82, v205, s[24:25]
	v_cmp_lt_i32_e64 s[24:25], 9, v165
	v_cndmask_b32_e64 v83, v83, v205, s[20:21]
	v_cmp_lt_i32_e64 s[20:21], 10, v165
	v_cndmask_b32_e64 v84, v84, v205, s[22:23]
	v_cmp_lt_i32_e64 s[22:23], 11, v165
	v_cndmask_b32_e64 v85, v85, v205, s[24:25]
	v_cmp_lt_i32_e64 s[24:25], 16, v165
	v_cndmask_b32_e64 v86, v86, v205, s[20:21]
	v_cmp_lt_i32_e64 s[20:21], 17, v165
	v_cndmask_b32_e64 v87, v87, v205, s[22:23]
	v_cmp_lt_i32_e64 s[22:23], 18, v165
	v_cndmask_b32_e64 v88, v88, v205, s[24:25]
	v_cmp_lt_i32_e64 s[24:25], 19, v165
	v_cndmask_b32_e64 v89, v89, v205, s[20:21]
	v_cmp_lt_i32_e64 s[20:21], 24, v165
	v_cndmask_b32_e64 v90, v90, v205, s[22:23]
	v_cmp_lt_i32_e64 s[22:23], 25, v165
	v_cndmask_b32_e64 v91, v91, v205, s[24:25]
	v_cmp_lt_i32_e64 s[24:25], 26, v165
	v_cndmask_b32_e64 v92, v92, v205, s[20:21]
	v_cmp_lt_i32_e64 s[20:21], 27, v165
	v_cndmask_b32_e64 v93, v93, v205, s[22:23]
	v_cmp_lt_i32_e64 s[22:23], 0, v166
	v_cndmask_b32_e64 v94, v94, v205, s[24:25]
	v_cmp_lt_i32_e64 s[24:25], 1, v166
	v_cndmask_b32_e64 v95, v95, v205, s[20:21]
	v_cmp_lt_i32_e64 s[20:21], 2, v166
	v_cndmask_b32_e64 v64, v64, v205, s[22:23]
	v_cmp_lt_i32_e64 s[22:23], 3, v166
	v_cndmask_b32_e64 v65, v65, v205, s[24:25]
	v_cmp_lt_i32_e64 s[24:25], 8, v166
	v_cndmask_b32_e64 v66, v66, v205, s[20:21]
	v_cmp_lt_i32_e64 s[20:21], 9, v166
	v_cndmask_b32_e64 v67, v67, v205, s[22:23]
	v_cmp_lt_i32_e64 s[22:23], 10, v166
	v_cndmask_b32_e64 v68, v68, v205, s[24:25]
	v_cmp_lt_i32_e64 s[24:25], 11, v166
	v_cndmask_b32_e64 v69, v69, v205, s[20:21]
	v_cmp_lt_i32_e64 s[20:21], 16, v166
	v_cndmask_b32_e64 v70, v70, v205, s[22:23]
	v_cmp_lt_i32_e64 s[22:23], 17, v166
	v_cndmask_b32_e64 v71, v71, v205, s[24:25]
	v_cmp_lt_i32_e64 s[24:25], 18, v166
	v_cndmask_b32_e64 v72, v72, v205, s[20:21]
	v_cmp_lt_i32_e64 s[20:21], 19, v166
	v_cndmask_b32_e64 v73, v73, v205, s[22:23]
	v_cmp_lt_i32_e64 s[22:23], 24, v166
	v_cndmask_b32_e64 v74, v74, v205, s[24:25]
	v_cmp_lt_i32_e64 s[24:25], 25, v166
	v_cndmask_b32_e64 v75, v75, v205, s[20:21]
	v_cmp_lt_i32_e64 s[20:21], 26, v166
	v_cndmask_b32_e64 v76, v76, v205, s[22:23]
	v_cmp_lt_i32_e64 s[22:23], 27, v166
	v_cndmask_b32_e64 v77, v77, v205, s[24:25]
	v_cndmask_b32_e64 v78, v78, v205, s[20:21]
	v_cndmask_b32_e64 v79, v79, v205, s[22:23]
	s_branch .LBB0_822
.Latt_m2:
	v_cmp_gt_i32_e64 s[20:21], 0, v165
	v_cmp_gt_i32_e64 s[22:23], 1, v165
	v_cmp_gt_i32_e64 s[24:25], 2, v165
	v_cndmask_b32_e64 v80, v80, v205, s[20:21]
	v_cmp_gt_i32_e64 s[20:21], 3, v165
	v_cndmask_b32_e64 v81, v81, v205, s[22:23]
	v_cmp_gt_i32_e64 s[22:23], 8, v165
	v_cndmask_b32_e64 v82, v82, v205, s[24:25]
	v_cmp_gt_i32_e64 s[24:25], 9, v165
	v_cndmask_b32_e64 v83, v83, v205, s[20:21]
	v_cmp_gt_i32_e64 s[20:21], 10, v165
	v_cndmask_b32_e64 v84, v84, v205, s[22:23]
	v_cmp_gt_i32_e64 s[22:23], 11, v165
	v_cndmask_b32_e64 v85, v85, v205, s[24:25]
	v_cmp_gt_i32_e64 s[24:25], 16, v165
	v_cndmask_b32_e64 v86, v86, v205, s[20:21]
	v_cmp_gt_i32_e64 s[20:21], 17, v165
	v_cndmask_b32_e64 v87, v87, v205, s[22:23]
	v_cmp_gt_i32_e64 s[22:23], 18, v165
	v_cndmask_b32_e64 v88, v88, v205, s[24:25]
	v_cmp_gt_i32_e64 s[24:25], 19, v165
	v_cndmask_b32_e64 v89, v89, v205, s[20:21]
	v_cmp_gt_i32_e64 s[20:21], 24, v165
	v_cndmask_b32_e64 v90, v90, v205, s[22:23]
	v_cmp_gt_i32_e64 s[22:23], 25, v165
	v_cndmask_b32_e64 v91, v91, v205, s[24:25]
	v_cmp_gt_i32_e64 s[24:25], 26, v165
	v_cndmask_b32_e64 v92, v92, v205, s[20:21]
	v_cmp_gt_i32_e64 s[20:21], 27, v165
	v_cndmask_b32_e64 v93, v93, v205, s[22:23]
	v_cmp_gt_i32_e64 s[22:23], 0, v166
	v_cndmask_b32_e64 v94, v94, v205, s[24:25]
	v_cmp_gt_i32_e64 s[24:25], 1, v166
	v_cndmask_b32_e64 v95, v95, v205, s[20:21]
	v_cmp_gt_i32_e64 s[20:21], 2, v166
	v_cndmask_b32_e64 v64, v64, v205, s[22:23]
	v_cmp_gt_i32_e64 s[22:23], 3, v166
	v_cndmask_b32_e64 v65, v65, v205, s[24:25]
	v_cmp_gt_i32_e64 s[24:25], 8, v166
	v_cndmask_b32_e64 v66, v66, v205, s[20:21]
	v_cmp_gt_i32_e64 s[20:21], 9, v166
	v_cndmask_b32_e64 v67, v67, v205, s[22:23]
	v_cmp_gt_i32_e64 s[22:23], 10, v166
	v_cndmask_b32_e64 v68, v68, v205, s[24:25]
	v_cmp_gt_i32_e64 s[24:25], 11, v166
	v_cndmask_b32_e64 v69, v69, v205, s[20:21]
	v_cmp_gt_i32_e64 s[20:21], 16, v166
	v_cndmask_b32_e64 v70, v70, v205, s[22:23]
	v_cmp_gt_i32_e64 s[22:23], 17, v166
	v_cndmask_b32_e64 v71, v71, v205, s[24:25]
	v_cmp_gt_i32_e64 s[24:25], 18, v166
	v_cndmask_b32_e64 v72, v72, v205, s[20:21]
	v_cmp_gt_i32_e64 s[20:21], 19, v166
	v_cndmask_b32_e64 v73, v73, v205, s[22:23]
	v_cmp_gt_i32_e64 s[22:23], 24, v166
	v_cndmask_b32_e64 v74, v74, v205, s[24:25]
	v_cmp_gt_i32_e64 s[24:25], 25, v166
	v_cndmask_b32_e64 v75, v75, v205, s[20:21]
	v_cmp_gt_i32_e64 s[20:21], 26, v166
	v_cndmask_b32_e64 v76, v76, v205, s[22:23]
	v_cmp_gt_i32_e64 s[22:23], 27, v166
	v_cndmask_b32_e64 v77, v77, v205, s[24:25]
	v_cndmask_b32_e64 v78, v78, v205, s[20:21]
	v_cndmask_b32_e64 v79, v79, v205, s[22:23]
.LBB0_822:
	s_nop 2
	v_max_f32_e32 v164, v81, v81
	v_max_f32_e32 v165, v80, v80
	v_max_f32_e32 v164, v165, v164
	v_max3_f32 v164, v164, v82, v83
	v_max3_f32 v164, v164, v84, v85
	v_max3_f32 v164, v164, v86, v87
	v_max3_f32 v164, v164, v88, v89
	v_max3_f32 v164, v164, v90, v91
	v_max3_f32 v164, v164, v92, v93
	v_max3_f32 v164, v164, v94, v95
	v_mov_b32_e32 v165, v164
	s_nop 1
	v_permlane32_swap_b32_e32 v164, v165
	v_max3_f32 v190, v159, v164, v165
	v_sub_f32_e32 v80, v80, v190
	v_sub_f32_e32 v81, v81, v190
	v_exp_f32_e32 v80, v80
	v_sub_f32_e32 v82, v82, v190
	v_exp_f32_e32 v81, v81
	v_sub_f32_e32 v83, v83, v190
	v_exp_f32_e32 v82, v82
	v_exp_f32_e32 v83, v83
	v_sub_f32_e32 v84, v84, v190
	v_sub_f32_e32 v164, v159, v190
	v_add_f32_e32 v159, 0, v80
	v_exp_f32_e32 v84, v84
	v_add_f32_e32 v159, v81, v159
	v_add_f32_e32 v159, v82, v159
	v_sub_f32_e32 v85, v85, v190
	v_add_f32_e32 v159, v83, v159
	v_exp_f32_e32 v85, v85
	v_add_f32_e32 v159, v84, v159
	v_cvt_pk_bf16_f32 v80, v80, v81
	v_cvt_pk_bf16_f32 v81, v82, v83
	v_cvt_pk_bf16_f32 v82, v84, v85
	v_max_f32_e32 v83, v65, v65
	v_max_f32_e32 v84, v64, v64
	v_max_f32_e32 v83, v84, v83
	v_max3_f32 v83, v83, v66, v67
	v_max3_f32 v83, v83, v68, v69
	v_max3_f32 v83, v83, v70, v71
	v_sub_f32_e32 v86, v86, v190
	v_max3_f32 v83, v83, v72, v73
	v_exp_f32_e32 v165, v86
	v_sub_f32_e32 v86, v87, v190
	v_max3_f32 v83, v83, v74, v75
	v_exp_f32_e32 v169, v86
	v_sub_f32_e32 v86, v88, v190
	v_max3_f32 v83, v83, v76, v77
	v_add_f32_e32 v193, v85, v159
	v_exp_f32_e32 v159, v86
	v_sub_f32_e32 v86, v89, v190
	v_max3_f32 v88, v83, v78, v79
	v_exp_f32_e32 v89, v86
	v_sub_f32_e32 v86, v90, v190
	v_mov_b32_e32 v90, v88
	v_exp_f32_e32 v167, v86
	v_sub_f32_e32 v86, v91, v190
	v_permlane32_swap_b32_e32 v88, v90
	v_exp_f32_e32 v91, v164
	v_exp_f32_e32 v171, v86
	v_max3_f32 v191, v158, v88, v90
	v_sub_f32_e32 v64, v64, v191
	v_exp_f32_e32 v194, v64
	v_sub_f32_e32 v64, v65, v191
	v_exp_f32_e32 v195, v64
	v_sub_f32_e32 v64, v66, v191
	v_exp_f32_e32 v196, v64
	v_sub_f32_e32 v64, v67, v191
	v_exp_f32_e32 v67, v64
	v_sub_f32_e32 v65, v68, v191
	v_add_f32_e32 v64, 0, v194
	v_exp_f32_e32 v68, v65
	v_sub_f32_e32 v65, v69, v191
	v_add_f32_e32 v64, v195, v64
	v_exp_f32_e32 v69, v65
	v_sub_f32_e32 v65, v70, v191
	v_add_f32_e32 v64, v196, v64
	v_exp_f32_e32 v164, v65
	v_sub_f32_e32 v65, v71, v191
	v_add_f32_e32 v64, v67, v64
	v_exp_f32_e32 v168, v65
	v_sub_f32_e32 v66, v72, v191
	v_sub_f32_e32 v90, v158, v191
	v_add_f32_e32 v64, v68, v64
	v_exp_f32_e32 v158, v66
	v_sub_f32_e32 v66, v73, v191
	v_add_f32_e32 v192, v69, v64
	v_exp_f32_e32 v88, v66
	v_sub_f32_e32 v66, v74, v191
	v_pk_add_f32 v[64:65], v[164:165], v[192:193]
	v_exp_f32_e32 v166, v66
	v_sub_f32_e32 v66, v75, v191
	v_sub_f32_e32 v86, v92, v190
	v_pk_add_f32 v[64:65], v[168:169], v[64:65]
	v_exp_f32_e32 v170, v66
	v_sub_f32_e32 v66, v76, v191
	v_exp_f32_e32 v173, v86
	v_sub_f32_e32 v86, v93, v190
	v_pk_add_f32 v[64:65], v[158:159], v[64:65]
	v_exp_f32_e32 v172, v66
	v_sub_f32_e32 v66, v77, v191
	v_exp_f32_e32 v93, v86
	v_sub_f32_e32 v86, v94, v190
	v_pk_add_f32 v[64:65], v[88:89], v[64:65]
	v_exp_f32_e32 v92, v66
	v_sub_f32_e32 v66, v78, v191
	v_exp_f32_e32 v175, v86
	v_sub_f32_e32 v86, v95, v190
	v_pk_add_f32 v[64:65], v[166:167], v[64:65]
	v_exp_f32_e32 v174, v66
	v_sub_f32_e32 v66, v79, v191
	v_exp_f32_e32 v95, v86
	v_pk_add_f32 v[64:65], v[170:171], v[64:65]
	v_exp_f32_e32 v94, v66
	v_pk_add_f32 v[64:65], v[172:173], v[64:65]
	v_exp_f32_e32 v90, v90
	v_pk_add_f32 v[64:65], v[92:93], v[64:65]
	v_mov_b32_e32 v66, v91
	v_pk_add_f32 v[64:65], v[174:175], v[64:65]
	v_cvt_pk_bf16_f32 v83, v165, v169
	v_cvt_pk_bf16_f32 v84, v159, v89
	v_cvt_pk_bf16_f32 v85, v167, v171
	v_cvt_pk_bf16_f32 v86, v173, v93
	v_cvt_pk_bf16_f32 v87, v175, v95
	s_nop 0
	v_pk_add_f32 v[64:65], v[94:95], v[64:65]
	v_pk_mul_f32 v[46:47], v[46:47], v[66:67] op_sel_hi:[1,0]
	v_pk_mul_f32 v[44:45], v[44:45], v[66:67] op_sel_hi:[1,0]
	v_pk_mul_f32 v[42:43], v[42:43], v[66:67] op_sel_hi:[1,0]
	v_pk_mul_f32 v[40:41], v[40:41], v[66:67] op_sel_hi:[1,0]
	v_pk_mul_f32 v[38:39], v[38:39], v[66:67] op_sel_hi:[1,0]
	v_pk_mul_f32 v[36:37], v[36:37], v[66:67] op_sel_hi:[1,0]
	v_pk_mul_f32 v[34:35], v[34:35], v[66:67] op_sel_hi:[1,0]
	v_pk_mul_f32 v[32:33], v[32:33], v[66:67] op_sel_hi:[1,0]
	v_pk_mul_f32 v[62:63], v[62:63], v[66:67] op_sel_hi:[1,0]
	v_pk_mul_f32 v[60:61], v[60:61], v[66:67] op_sel_hi:[1,0]
	v_pk_mul_f32 v[58:59], v[58:59], v[66:67] op_sel_hi:[1,0]
	v_pk_mul_f32 v[56:57], v[56:57], v[66:67] op_sel_hi:[1,0]
	v_pk_mul_f32 v[54:55], v[54:55], v[66:67] op_sel_hi:[1,0]
	v_pk_mul_f32 v[52:53], v[52:53], v[66:67] op_sel_hi:[1,0]
	v_pk_mul_f32 v[50:51], v[50:51], v[66:67] op_sel_hi:[1,0]
	v_pk_mul_f32 v[48:49], v[48:49], v[66:67] op_sel_hi:[1,0]
	v_pk_fma_f32 v[148:149], v[148:149], v[90:91], v[64:65]
	v_cvt_pk_bf16_f32 v64, v194, v195
	v_cvt_pk_bf16_f32 v65, v196, v67
	v_cvt_pk_bf16_f32 v66, v68, v69
	v_cvt_pk_bf16_f32 v67, v164, v168
	v_cvt_pk_bf16_f32 v68, v158, v88
	v_cvt_pk_bf16_f32 v69, v166, v170
	v_cvt_pk_bf16_f32 v70, v172, v92
	v_cvt_pk_bf16_f32 v71, v174, v94
	ds_read2_b64 v[72:75], v188 offset1:2
	v_add_u32_e32 v164, 0x2000, v188
	ds_read2_b64 v[76:79], v164 offset0:32 offset1:34
	ds_read2_b64 v[168:171], v188 offset0:4 offset1:6
	ds_read2_b64 v[92:95], v164 offset0:36 offset1:38
	v_pk_mul_f32 v[30:31], v[30:31], v[90:91] op_sel_hi:[1,0]
	v_pk_mul_f32 v[28:29], v[28:29], v[90:91] op_sel_hi:[1,0]
	v_pk_mul_f32 v[26:27], v[26:27], v[90:91] op_sel_hi:[1,0]
	v_pk_mul_f32 v[24:25], v[24:25], v[90:91] op_sel_hi:[1,0]
	v_pk_mul_f32 v[22:23], v[22:23], v[90:91] op_sel_hi:[1,0]
	v_pk_mul_f32 v[20:21], v[20:21], v[90:91] op_sel_hi:[1,0]
	v_pk_mul_f32 v[18:19], v[18:19], v[90:91] op_sel_hi:[1,0]
	v_pk_mul_f32 v[16:17], v[16:17], v[90:91] op_sel_hi:[1,0]
	v_pk_mul_f32 v[14:15], v[14:15], v[90:91] op_sel_hi:[1,0]
	v_pk_mul_f32 v[12:13], v[12:13], v[90:91] op_sel_hi:[1,0]
	v_pk_mul_f32 v[10:11], v[10:11], v[90:91] op_sel_hi:[1,0]
	v_pk_mul_f32 v[8:9], v[8:9], v[90:91] op_sel_hi:[1,0]
	v_pk_mul_f32 v[6:7], v[6:7], v[90:91] op_sel_hi:[1,0]
	v_pk_mul_f32 v[4:5], v[4:5], v[90:91] op_sel_hi:[1,0]
	v_pk_mul_f32 v[2:3], v[2:3], v[90:91] op_sel_hi:[1,0]
	v_pk_mul_f32 v[0:1], v[0:1], v[90:91] op_sel_hi:[1,0]
	s_setprio 1
	s_waitcnt lgkmcnt(3)
	v_mfma_f32_32x32x16_bf16 v[32:47], v[72:75], v[80:83], v[32:47]
	v_mfma_f32_32x32x16_bf16 v[16:31], v[72:75], v[64:67], v[16:31]
	s_waitcnt lgkmcnt(2)
	v_mfma_f32_32x32x16_bf16 v[48:63], v[76:79], v[80:83], v[48:63]
	v_mfma_f32_32x32x16_bf16 v[0:15], v[76:79], v[64:67], v[0:15]
	s_waitcnt lgkmcnt(1)
	v_mfma_f32_32x32x16_bf16 v[32:47], v[168:171], v[84:87], v[32:47]
	v_mfma_f32_32x32x16_bf16 v[16:31], v[168:171], v[68:71], v[16:31]
	s_waitcnt lgkmcnt(0)
	v_mfma_f32_32x32x16_bf16 v[48:63], v[92:95], v[84:87], v[48:63]
	v_mfma_f32_32x32x16_bf16 v[0:15], v[92:95], v[68:71], v[0:15]
	s_setprio 0
	s_add_i32 s13, s13, 32
	v_add_u32_e32 v188, 64, v188
	s_cmpk_eq_i32 s13, 0x80
	v_add_u32_e32 v189, 0x1200, v189
	s_cbranch_scc1 .LBB0_824
	v_mov_b32_e32 v158, v191
	v_mov_b32_e32 v159, v190
	s_branch .LBB0_816

.LBB0_828:
	v_readlane_b32 s20, v242, 21
	v_readlane_b32 s21, v242, 22
	v_readlane_b32 s22, v242, 23
	v_readlane_b32 s23, v242, 24
	v_readlane_b32 s24, v242, 25
	v_readlane_b32 s25, v242, 26
	s_waitcnt vmcnt(0)
	s_waitcnt vmcnt(0) lgkmcnt(0)
	s_barrier
	s_mov_b64 s[2:3], exec
	v_readlane_b32 s4, v247, 0
	v_readlane_b32 s5, v247, 1
	v_readlane_b32 s6, v242, 3
	s_and_b64 s[4:5], s[2:3], s[4:5]
	v_readlane_b32 s7, v242, 4
	s_mov_b64 exec, s[4:5]
	s_cbranch_execz .LBB0_880
	v_readlane_b32 s4, v243, 47
	s_waitcnt vmcnt(0) expcnt(0) lgkmcnt(0)
	s_nop 0
	v_mov_b32_e32 v0, s4
	ds_read_b32 v2, v0
	v_readlane_b32 s4, v243, 48
	s_waitcnt lgkmcnt(0)
	v_cmp_ne_u32_e32 vcc, 0, v2
	v_mov_b32_e32 v0, s4
	ds_read_b32 v0, v0
	s_cbranch_vccnz .LBB0_844
	s_mov_b32 s4, 1
	s_branch .LBB0_832
